# barrier leader path: drop the per-XCD generation-word atomic nobody waits on (dead-work removal) on top of the normmod1 version
# speedup vs baseline: 1.0033x; 1.0033x over previous
; __device__ __forceinline__ unsigned xb_add(unsigned* p, unsigned v) { return __hip_atomic_fetch_add(p, v, __ATOMIC_RELAXED, __HIP_MEMORY_SCOPE_AGENT); }
; __device__ __forceinline__ void xcd_barrier(const XcdBarrier& b) {
;     ...
;             __builtin_amdgcn_fence(__ATOMIC_ACQUIRE, "agent");
;             xb_add(&bar[XB_XGEN(b.x)], 1u);
;             asm volatile("s_waitcnt vmcnt(0)" ::: "memory");
.LBB0_124:
	s_or_b64 exec, exec, s[8:9]
	s_mov_b64 s[8:9], exec
	v_mbcnt_lo_u32_b32 v0, s8, 0
	v_mbcnt_hi_u32_b32 v0, s9, v0
	v_cmp_eq_u32_e32 vcc, 0, v0
	s_waitcnt vmcnt(0)
	buffer_inv sc1
	s_and_saveexec_b64 s[10:11], vcc
	s_cbranch_execz .LBB0_126
	s_bcnt1_i32_b64 s2, s[8:9]
	v_mov_b32_e32 v0, 0x2000
	v_mov_b32_e32 v1, s2
.LBB0_126:
	s_or_b64 exec, exec, s[10:11]
	s_waitcnt vmcnt(0)

; __device__ __forceinline__ unsigned xb_add(unsigned* p, unsigned v) { return __hip_atomic_fetch_add(p, v, __ATOMIC_RELAXED, __HIP_MEMORY_SCOPE_AGENT); }
; __device__ __forceinline__ void xcd_barrier(const XcdBarrier& b) {
;     ...
;             __builtin_amdgcn_fence(__ATOMIC_ACQUIRE, "agent");
;             xb_add(&bar[XB_XGEN(b.x)], 1u);
;             asm volatile("s_waitcnt vmcnt(0)" ::: "memory");
.LBB0_179:
	s_or_b64 exec, exec, s[8:9]
	s_mov_b64 s[8:9], exec
	v_mbcnt_lo_u32_b32 v0, s8, 0
	v_mbcnt_hi_u32_b32 v0, s9, v0
	v_cmp_eq_u32_e32 vcc, 0, v0
	s_waitcnt vmcnt(0)
	buffer_inv sc1
	s_and_saveexec_b64 s[10:11], vcc
	s_cbranch_execz .LBB0_181
	s_bcnt1_i32_b64 s2, s[8:9]
	v_mov_b32_e32 v0, 0x2000
	v_mov_b32_e32 v1, s2
.LBB0_181:
	s_or_b64 exec, exec, s[10:11]
	s_waitcnt vmcnt(0)

; __device__ __forceinline__ unsigned xb_add(unsigned* p, unsigned v) { return __hip_atomic_fetch_add(p, v, __ATOMIC_RELAXED, __HIP_MEMORY_SCOPE_AGENT); }
; __device__ __forceinline__ void xcd_barrier(const XcdBarrier& b) {
;     ...
;             __builtin_amdgcn_fence(__ATOMIC_ACQUIRE, "agent");
;             xb_add(&bar[XB_XGEN(b.x)], 1u);
;             asm volatile("s_waitcnt vmcnt(0)" ::: "memory");
.LBB0_247:
	s_or_b64 exec, exec, s[8:9]
	s_mov_b64 s[8:9], exec
	v_mbcnt_lo_u32_b32 v0, s8, 0
	v_mbcnt_hi_u32_b32 v0, s9, v0
	v_cmp_eq_u32_e32 vcc, 0, v0
	s_waitcnt vmcnt(0)
	buffer_inv sc1
	s_and_saveexec_b64 s[12:13], vcc
	s_cbranch_execz .LBB0_249
	s_bcnt1_i32_b64 s2, s[8:9]
	v_mov_b32_e32 v0, 0x2000
	v_mov_b32_e32 v1, s2
.LBB0_249:
	s_or_b64 exec, exec, s[12:13]
	s_waitcnt vmcnt(0)

; __device__ __forceinline__ unsigned xb_add(unsigned* p, unsigned v) { return __hip_atomic_fetch_add(p, v, __ATOMIC_RELAXED, __HIP_MEMORY_SCOPE_AGENT); }
; __device__ __forceinline__ void xcd_barrier(const XcdBarrier& b) {
;     ...
;             __builtin_amdgcn_fence(__ATOMIC_ACQUIRE, "agent");
;             xb_add(&bar[XB_XGEN(b.x)], 1u);
;             asm volatile("s_waitcnt vmcnt(0)" ::: "memory");
.LBB0_329:
	s_or_b64 exec, exec, s[14:15]
	s_mov_b64 s[14:15], exec
	v_mbcnt_lo_u32_b32 v0, s14, 0
	v_mbcnt_hi_u32_b32 v0, s15, v0
	v_cmp_eq_u32_e32 vcc, 0, v0
	s_waitcnt vmcnt(0)
	buffer_inv sc1
	s_and_saveexec_b64 s[16:17], vcc
	s_cbranch_execz .LBB0_331
	s_bcnt1_i32_b64 s2, s[14:15]
	v_mov_b32_e32 v0, 0x2000
	v_mov_b32_e32 v1, s2
.LBB0_331:
	s_or_b64 exec, exec, s[16:17]
	s_waitcnt vmcnt(0)

; __device__ __forceinline__ unsigned xb_add(unsigned* p, unsigned v) { return __hip_atomic_fetch_add(p, v, __ATOMIC_RELAXED, __HIP_MEMORY_SCOPE_AGENT); }
; __device__ __forceinline__ void xcd_barrier(const XcdBarrier& b) {
;     ...
;             __builtin_amdgcn_fence(__ATOMIC_ACQUIRE, "agent");
;             xb_add(&bar[XB_XGEN(b.x)], 1u);
;             asm volatile("s_waitcnt vmcnt(0)" ::: "memory");
.LBB0_383:
	s_or_b64 exec, exec, s[4:5]
	v_mov_b32_e32 v0, 1
	s_waitcnt vmcnt(0)
	buffer_inv sc1
	s_waitcnt vmcnt(0)

; __device__ __forceinline__ unsigned xb_add(unsigned* p, unsigned v) { return __hip_atomic_fetch_add(p, v, __ATOMIC_RELAXED, __HIP_MEMORY_SCOPE_AGENT); }
; __device__ __forceinline__ void xcd_barrier(const XcdBarrier& b) {
;     ...
;             __builtin_amdgcn_fence(__ATOMIC_ACQUIRE, "agent");
;             xb_add(&bar[XB_XGEN(b.x)], 1u);
;             asm volatile("s_waitcnt vmcnt(0)" ::: "memory");
.LBB0_517:
	s_or_b64 exec, exec, s[8:9]
	v_mov_b32_e32 v0, 1
	s_waitcnt vmcnt(0)
	buffer_inv sc1
	s_waitcnt vmcnt(0)
